# context rows of out-proj / FFN-down GEMMs: register-direct streaming 16x16 tiles on all workgroups instead of 128x32 LDS tiles on a quarter of them
# baseline (speedup 1.0000x reference)
.LBB0_52:
	s_andn2_b64 vcc, exec, s[2:3]
	s_cbranch_vccnz .LBB0_57
	v_readlane_b32 s2, v252, 20
	v_readlane_b32 s3, v252, 21
	v_readlane_b32 s5, v255, 19
	v_readlane_b32 s8, v252, 0
	s_nop 0
	s_sub_u32 s2, s2, 0x1c0
	s_subb_u32 s3, s3, 0
	s_sub_i32 s5, s5, 3
	s_lshr_b32 s5, s5, 3
	v_and_b32_e32 v0, 63, v220
	v_and_b32_e32 v1, 15, v0
	v_lshrrev_b32_e32 v12, 4, v0
	v_lshrrev_b32_e32 v13, 6, v220
	v_lshrrev_b32_e32 v14, 1, v13
	v_and_b32_e32 v13, 1, v13
	s_and_b32 s10, s8, 31
	s_lshl_b32 s10, s10, 5
	s_lshr_b32 s11, s8, 5
	s_lshl_b32 s11, s11, 5
	s_addk_i32 s11, 0x4000
	v_lshlrev_b32_e32 v14, 4, v14
	v_add_u32_e32 v14, s10, v14
	v_add_u32_e32 v15, v14, v1
	v_lshl_add_u32 v13, v13, 4, v1
	v_add_u32_e32 v13, s11, v13
	s_mov_b32 s10, 0x1600
	v_lshlrev_b32_e32 v16, 4, v12
	v_mul_lo_u32 v15, v15, s10
	v_mul_lo_u32 v17, v13, s10
	v_add_u32_e32 v15, v15, v16
	v_add_u32_e32 v17, v17, v16
	v_lshl_add_u32 v14, v12, 2, v14
	v_lshlrev_b32_e32 v13, 10, v13
	v_add_u32_e32 v13, v13, v14
	v_lshlrev_b32_e32 v13, 1, v13
	s_load_dwordx2 s[10:11], s[2:3], 0x100
	s_mul_i32 s8, s5, 0x580000
	s_waitcnt lgkmcnt(0)
	s_add_u32 s10, s10, s8
	s_addc_u32 s11, s11, 0
	v_mov_b32_e32 v192, v15
	v_lshl_add_u64 v[2:3], v[192:193], 0, s[10:11]
	s_load_dwordx2 s[10:11], s[2:3], 0x1a0
	s_waitcnt lgkmcnt(0)
	v_mov_b32_e32 v192, v17
	v_lshl_add_u64 v[4:5], v[192:193], 0, s[10:11]
	s_load_dwordx2 s[10:11], s[2:3], 0x140
	s_waitcnt lgkmcnt(0)
	v_mov_b32_e32 v192, v13
	v_lshl_add_u64 v[6:7], v[192:193], 0, s[10:11]
	v_mov_b32_e32 v8, 0
	v_mov_b32_e32 v9, 0
	v_mov_b32_e32 v10, 0
	v_mov_b32_e32 v11, 0
	global_load_dwordx4 v[122:125], v[2:3], off
	global_load_dwordx4 v[126:129], v[4:5], off
	global_load_dwordx4 v[130:133], v[2:3], off offset:64
	global_load_dwordx4 v[134:137], v[4:5], off offset:64
	global_load_dwordx4 v[138:141], v[2:3], off offset:128
	global_load_dwordx4 v[142:145], v[4:5], off offset:128
	global_load_dwordx4 v[146:149], v[2:3], off offset:192
	global_load_dwordx4 v[150:153], v[4:5], off offset:192
	global_load_dwordx4 v[154:157], v[2:3], off offset:256
	global_load_dwordx4 v[158:161], v[4:5], off offset:256
	global_load_dwordx4 v[162:165], v[2:3], off offset:320
	global_load_dwordx4 v[166:169], v[4:5], off offset:320
	global_load_dwordx4 v[170:173], v[2:3], off offset:384
	global_load_dwordx4 v[174:177], v[4:5], off offset:384
	global_load_dwordx4 v[178:181], v[2:3], off offset:448
	global_load_dwordx4 v[182:185], v[4:5], off offset:448
	s_mov_b32 s8, 10
	s_mov_b64 s[10:11], 0x200
.Lctxd_loop:
	v_lshl_add_u64 v[2:3], v[2:3], 0, s[10:11]
	v_lshl_add_u64 v[4:5], v[4:5], 0, s[10:11]
	s_waitcnt vmcnt(12)
	v_mfma_f32_16x16x32_bf16 v[8:11], v[122:125], v[126:129], v[8:11]
	v_mfma_f32_16x16x32_bf16 v[8:11], v[130:133], v[134:137], v[8:11]
	global_load_dwordx4 v[122:125], v[2:3], off
	global_load_dwordx4 v[126:129], v[4:5], off
	global_load_dwordx4 v[130:133], v[2:3], off offset:64
	global_load_dwordx4 v[134:137], v[4:5], off offset:64
	s_waitcnt vmcnt(12)
	v_mfma_f32_16x16x32_bf16 v[8:11], v[138:141], v[142:145], v[8:11]
	v_mfma_f32_16x16x32_bf16 v[8:11], v[146:149], v[150:153], v[8:11]
	global_load_dwordx4 v[138:141], v[2:3], off offset:128
	global_load_dwordx4 v[142:145], v[4:5], off offset:128
	global_load_dwordx4 v[146:149], v[2:3], off offset:192
	global_load_dwordx4 v[150:153], v[4:5], off offset:192
	s_waitcnt vmcnt(12)
	v_mfma_f32_16x16x32_bf16 v[8:11], v[154:157], v[158:161], v[8:11]
	v_mfma_f32_16x16x32_bf16 v[8:11], v[162:165], v[166:169], v[8:11]
	global_load_dwordx4 v[154:157], v[2:3], off offset:256
	global_load_dwordx4 v[158:161], v[4:5], off offset:256
	global_load_dwordx4 v[162:165], v[2:3], off offset:320
	global_load_dwordx4 v[166:169], v[4:5], off offset:320
	s_waitcnt vmcnt(12)
	v_mfma_f32_16x16x32_bf16 v[8:11], v[170:173], v[174:177], v[8:11]
	v_mfma_f32_16x16x32_bf16 v[8:11], v[178:181], v[182:185], v[8:11]
	global_load_dwordx4 v[170:173], v[2:3], off offset:384
	global_load_dwordx4 v[174:177], v[4:5], off offset:384
	global_load_dwordx4 v[178:181], v[2:3], off offset:448
	global_load_dwordx4 v[182:185], v[4:5], off offset:448
	s_sub_i32 s8, s8, 1
	s_cmp_lg_u32 s8, 0
	s_cbranch_scc1 .Lctxd_loop
	s_waitcnt vmcnt(12)
	v_mfma_f32_16x16x32_bf16 v[8:11], v[122:125], v[126:129], v[8:11]
	v_mfma_f32_16x16x32_bf16 v[8:11], v[130:133], v[134:137], v[8:11]
	s_waitcnt vmcnt(8)
	v_mfma_f32_16x16x32_bf16 v[8:11], v[138:141], v[142:145], v[8:11]
	v_mfma_f32_16x16x32_bf16 v[8:11], v[146:149], v[150:153], v[8:11]
	s_waitcnt vmcnt(4)
	v_mfma_f32_16x16x32_bf16 v[8:11], v[154:157], v[158:161], v[8:11]
	v_mfma_f32_16x16x32_bf16 v[8:11], v[162:165], v[166:169], v[8:11]
	s_waitcnt vmcnt(0)
	v_mfma_f32_16x16x32_bf16 v[8:11], v[170:173], v[174:177], v[8:11]
	v_mfma_f32_16x16x32_bf16 v[8:11], v[178:181], v[182:185], v[8:11]
	s_nop 9
	v_cvt_pk_bf16_f32 v12, v8, v9
	v_cvt_pk_bf16_f32 v13, v10, v11
	global_store_dwordx2 v[6:7], v[12:13], off
	s_branch .LBB0_57

.LBB0_90:
	s_andn2_b64 vcc, exec, s[2:3]
	s_cbranch_vccnz .LBB0_93
	v_readlane_b32 s2, v252, 20
	v_readlane_b32 s3, v252, 21
	v_readlane_b32 s5, v255, 19
	v_readlane_b32 s8, v252, 0
	s_nop 0
	s_sub_u32 s2, s2, 0x1c0
	s_subb_u32 s3, s3, 0
	s_sub_i32 s5, s5, 3
	s_lshr_b32 s5, s5, 3
	v_and_b32_e32 v0, 63, v220
	v_and_b32_e32 v1, 15, v0
	v_lshrrev_b32_e32 v12, 4, v0
	v_lshrrev_b32_e32 v13, 6, v220
	v_lshrrev_b32_e32 v14, 1, v13
	v_and_b32_e32 v13, 1, v13
	s_and_b32 s10, s8, 31
	s_lshl_b32 s10, s10, 5
	s_lshr_b32 s11, s8, 5
	s_lshl_b32 s11, s11, 5
	s_addk_i32 s11, 0x4000
	v_lshlrev_b32_e32 v14, 4, v14
	v_add_u32_e32 v14, s10, v14
	v_add_u32_e32 v15, v14, v1
	v_lshl_add_u32 v13, v13, 4, v1
	v_add_u32_e32 v13, s11, v13
	s_mov_b32 s10, 0x800
	v_lshlrev_b32_e32 v16, 4, v12
	v_mul_lo_u32 v15, v15, s10
	v_mul_lo_u32 v17, v13, s10
	v_add_u32_e32 v15, v15, v16
	v_add_u32_e32 v17, v17, v16
	v_lshl_add_u32 v14, v12, 2, v14
	v_lshlrev_b32_e32 v13, 10, v13
	v_add_u32_e32 v13, v13, v14
	v_lshlrev_b32_e32 v13, 1, v13
	s_load_dwordx2 s[10:11], s[2:3], 0xf0
	s_mul_i32 s8, s5, 0x200000
	s_waitcnt lgkmcnt(0)
	s_add_u32 s10, s10, s8
	s_addc_u32 s11, s11, 0
	v_mov_b32_e32 v192, v15
	v_lshl_add_u64 v[2:3], v[192:193], 0, s[10:11]
	s_load_dwordx2 s[10:11], s[2:3], 0x148
	s_waitcnt lgkmcnt(0)
	v_mov_b32_e32 v192, v17
	v_lshl_add_u64 v[4:5], v[192:193], 0, s[10:11]
	s_load_dwordx2 s[10:11], s[2:3], 0x140
	s_waitcnt lgkmcnt(0)
	v_mov_b32_e32 v192, v13
	v_lshl_add_u64 v[6:7], v[192:193], 0, s[10:11]
	v_mov_b32_e32 v8, 0
	v_mov_b32_e32 v9, 0
	v_mov_b32_e32 v10, 0
	v_mov_b32_e32 v11, 0
	global_load_dwordx4 v[122:125], v[2:3], off
	global_load_dwordx4 v[126:129], v[4:5], off
	global_load_dwordx4 v[130:133], v[2:3], off offset:64
	global_load_dwordx4 v[134:137], v[4:5], off offset:64
	global_load_dwordx4 v[138:141], v[2:3], off offset:128
	global_load_dwordx4 v[142:145], v[4:5], off offset:128
	global_load_dwordx4 v[146:149], v[2:3], off offset:192
	global_load_dwordx4 v[150:153], v[4:5], off offset:192
	global_load_dwordx4 v[154:157], v[2:3], off offset:256
	global_load_dwordx4 v[158:161], v[4:5], off offset:256
	global_load_dwordx4 v[162:165], v[2:3], off offset:320
	global_load_dwordx4 v[166:169], v[4:5], off offset:320
	global_load_dwordx4 v[170:173], v[2:3], off offset:384
	global_load_dwordx4 v[174:177], v[4:5], off offset:384
	global_load_dwordx4 v[178:181], v[2:3], off offset:448
	global_load_dwordx4 v[182:185], v[4:5], off offset:448
	s_mov_b32 s8, 3
	s_mov_b64 s[10:11], 0x200
